# MLA projection epilogue: rope (cos, sin) table staged once per phase in unused LDS; rope sites read it with ds_read2_b64 and wait lgkmcnt only, so a tile's stores no longer serialise
# speedup vs baseline: 1.0030x; 1.0030x over previous
.LBB0_713:
	v_readlane_b32 s6, v254, 25
	v_readlane_b32 s7, v254, 26
	s_load_dwordx2 s[6:7], s[6:7], 0x118
	v_lshl_add_u64 v[8:9], v[8:9], 0, s[92:93]
	s_waitcnt vmcnt(4)
	s_barrier
	v_lshl_add_u64 v[6:7], v[6:7], 0, s[92:93]
	s_waitcnt lgkmcnt(0)
	s_add_u32 s16, s6, 0xcd54000
	s_addc_u32 s17, s7, 0
	s_add_u32 s18, s6, 0xdf54000
	s_addc_u32 s19, s7, 0
	s_add_u32 s20, s6, 0x5000
	s_addc_u32 s21, s7, 0
	v_lshlrev_b32_e32 v142, 3, v163
	global_load_dwordx2 v[140:141], v142, s[20:21]
	v_add_u32_e32 v142, 0x20000, v142
	s_waitcnt vmcnt(0)
	ds_write_b64 v142, v[140:141]
	s_waitcnt lgkmcnt(0)
	s_lshl_b32 s6, s4, 13
	s_lshl_b32 s4, s5, 12
	s_add_i32 m0, s36, 0x18000
	s_and_b32 s7, s4, 0x3000
	global_load_lds_dwordx4 v[8:9], off
	s_add_i32 m0, s36, 0x1a000
	s_add_i32 s40, s36, 0x8000
	s_add_i32 s41, s36, 0xa000
	global_load_lds_dwordx4 v[6:7], off
	v_lshl_add_u64 v[4:5], v[4:5], 0, s[92:93]
	s_mov_b32 m0, s40
	s_add_u32 s4, s12, 0x18080
	global_load_lds_dwordx4 v[4:5], off
	v_lshl_add_u64 v[2:3], v[2:3], 0, s[92:93]
	s_mov_b32 m0, s41
	s_addc_u32 s5, s13, 0
	global_load_lds_dwordx4 v[2:3], off
	s_add_i32 m0, s36, 0x1c000
	v_lshl_add_u64 v[2:3], s[4:5], 0, v[130:131]
	global_load_lds_dwordx4 v[2:3], off
	v_lshl_add_u64 v[2:3], s[4:5], 0, v[132:133]
	s_add_i32 m0, s36, 0x1e000
	s_mov_b64 s[8:9], 0x18080
	global_load_lds_dwordx4 v[2:3], off
	v_and_b32_e32 v2, 15, v0
	v_and_b32_e32 v3, 48, v0
	v_lshlrev_b32_e32 v2, 6, v2
	v_lshlrev_b32_e32 v0, 2, v0
	v_or_b32_e32 v4, v2, v3
	v_and_b32_e32 v0, 32, v0
	v_bitop3_b32 v2, v2, v0, v3 bitop3:0x36
	v_bitop3_b32 v4, v4, s6, v0 bitop3:0xde
	s_movk_i32 s6, 0x180
	v_or_b32_e32 v146, s7, v2
	v_lshrrev_b32_e32 v2, 1, v14
	v_mul_lo_u32 v0, v16, s6
	s_movk_i32 s7, 0x1800
	v_mad_u64_u32 v[2:3], s[4:5], v2, s7, v[0:1]
	v_or_b32_e32 v0, v2, v15
	v_add_lshl_u32 v0, v0, v17, 1
	v_lshl_add_u64 v[134:135], v[0:1], 0, s[8:9]
	v_lshrrev_b32_e32 v2, 1, v10
	v_mul_lo_u32 v0, v12, s6
	v_mad_u64_u32 v[2:3], s[4:5], v2, s7, v[0:1]
	s_waitcnt vmcnt(6)
	v_or_b32_e32 v0, v2, v11
	v_add_lshl_u32 v0, v0, v13, 1
	s_ashr_i32 s42, s0, 31
	s_ashr_i32 s43, s1, 31
	v_lshl_add_u64 v[136:137], v[0:1], 0, s[8:9]
	s_mov_b32 s44, 0
	v_add_u32_e32 v147, 0, v4
	s_barrier
	s_branch .LBB0_717

.LBB0_729:
	s_or_saveexec_b64 s[12:13], s[12:13]
	s_movk_i32 s26, 0x300
	v_bfe_u32 v141, v140, 6, 5
	v_mad_i64_i32 v[142:143], s[26:27], v140, s26, 0
	s_xor_b64 exec, exec, s[12:13]
	s_cbranch_execz .LBB0_735
	s_and_saveexec_b64 s[26:27], s[10:11]
	s_cbranch_execz .LBB0_734
	s_mov_b32 s28, 0x2aaaaaab
	v_mul_hi_i32 v0, v138, s28
	v_lshrrev_b32_e32 v139, 31, v0
	v_lshrrev_b32_e32 v0, 4, v0
	v_add_u32_e32 v0, v0, v139
	s_movk_i32 s28, 0x60
	v_mul_lo_u32 v0, v0, s28
	v_sub_u32_e32 v139, v138, v0
	v_cmp_lt_i32_e32 vcc, 63, v139
	s_and_b64 s[30:31], s[8:9], vcc
	s_and_saveexec_b64 s[28:29], s[30:31]
	s_cbranch_execz .LBB0_733
	v_and_b32_e32 v0, 0x7ffffff0, v139
	v_cmp_eq_u32_e32 vcc, 64, v0
	s_nop 1
	v_cndmask_b32_e32 v0, v149, v141, vcc
	v_lshlrev_b32_e32 v0, 6, v0
	v_add_u32_e32 v150, 0x20000, v0
	v_lshlrev_b32_e32 v0, 2, v139
	v_and_b32_e32 v0, 32, v0
	v_add_u32_e32 v154, v150, v0
	ds_read2_b64 v[150:153], v154 offset0:2 offset1:3
	ds_read2_b64 v[154:157], v154 offset1:1
	s_waitcnt lgkmcnt(0)
	v_pk_mul_f32 v[176:177], v[122:123], v[150:151] op_sel:[1,1] op_sel_hi:[1,0]
	v_pk_mul_f32 v[160:161], v[126:127], v[154:155] op_sel:[1,1] op_sel_hi:[1,0]
	v_mul_f32_e32 v0, v129, v157
	v_pk_mul_f32 v[158:159], v[126:127], v[154:155]
	v_pk_fma_f32 v[126:127], v[126:127], v[154:155], v[160:161] op_sel_hi:[0,1,1]
	v_pk_fma_f32 v[154:155], v[128:129], v[156:157], v[0:1] op_sel_hi:[1,1,0] neg_lo:[0,0,1] neg_hi:[0,0,1]
	v_mul_f32_e32 v0, v129, v156
	v_pk_fma_f32 v[156:157], v[128:129], v[156:157], v[0:1] op_sel:[0,1,0] op_sel_hi:[1,0,0]
	v_mul_f32_e32 v0, v125, v153
	v_pk_mul_f32 v[128:129], v[122:123], v[150:151]
	v_pk_fma_f32 v[122:123], v[122:123], v[150:151], v[176:177] op_sel_hi:[0,1,1]
	v_pk_fma_f32 v[150:151], v[124:125], v[152:153], v[0:1] op_sel_hi:[1,1,0] neg_lo:[0,0,1] neg_hi:[0,0,1]
	v_mul_f32_e32 v0, v125, v152
	v_pk_fma_f32 v[152:153], v[124:125], v[152:153], v[0:1] op_sel:[0,1,0] op_sel_hi:[1,0,0]
	v_sub_f32_e32 v122, v128, v176
	v_sub_f32_e32 v126, v158, v160
	v_mov_b32_e32 v124, v150
	v_mov_b32_e32 v125, v152
	v_mov_b32_e32 v128, v154
	v_mov_b32_e32 v129, v156

.LBB0_739:
	s_andn2_saveexec_b64 s[12:13], s[26:27]
	s_cbranch_execz .LBB0_745
	s_and_saveexec_b64 s[26:27], s[10:11]
	s_cbranch_execz .LBB0_744
	s_mov_b32 s10, 0x2aaaaaab
	v_mul_hi_i32 v0, v122, s10
	v_lshrrev_b32_e32 v123, 31, v0
	v_lshrrev_b32_e32 v0, 4, v0
	v_add_u32_e32 v0, v0, v123
	s_movk_i32 s10, 0x60
	v_mul_lo_u32 v0, v0, s10
	v_sub_u32_e32 v123, v122, v0
	v_cmp_lt_i32_e64 s[10:11], 63, v123
	s_and_b64 s[8:9], s[8:9], s[10:11]
	s_and_saveexec_b64 s[10:11], s[8:9]
	s_cbranch_execz .LBB0_743
	v_and_b32_e32 v0, 0x7ffffff0, v123
	v_cmp_eq_u32_e64 s[8:9], 64, v0
	s_nop 1
	v_cndmask_b32_e64 v0, v149, v141, s[8:9]
	v_lshlrev_b32_e32 v0, 6, v0
	v_add_u32_e32 v124, 0x20000, v0
	v_lshlrev_b32_e32 v0, 2, v123
	v_and_b32_e32 v0, 56, v0
	v_add_u32_e32 v128, v124, v0
	ds_read2_b64 v[124:127], v128 offset0:2 offset1:3
	ds_read2_b64 v[150:153], v128 offset1:1
	s_waitcnt lgkmcnt(0)
	v_pk_mul_f32 v[154:155], v[114:115], v[124:125] op_sel:[1,1] op_sel_hi:[1,0]
	v_pk_mul_f32 v[144:145], v[118:119], v[150:151] op_sel:[1,1] op_sel_hi:[1,0]
	v_mul_f32_e32 v0, v121, v153
	v_pk_mul_f32 v[128:129], v[118:119], v[150:151]
	v_pk_fma_f32 v[118:119], v[118:119], v[150:151], v[144:145] op_sel_hi:[0,1,1]
	v_pk_fma_f32 v[150:151], v[120:121], v[152:153], v[0:1] op_sel_hi:[1,1,0] neg_lo:[0,0,1] neg_hi:[0,0,1]
	v_mul_f32_e32 v0, v121, v152
	v_pk_fma_f32 v[152:153], v[120:121], v[152:153], v[0:1] op_sel:[0,1,0] op_sel_hi:[1,0,0]
	v_mul_f32_e32 v0, v117, v127
	v_pk_mul_f32 v[120:121], v[114:115], v[124:125]
	v_pk_fma_f32 v[114:115], v[114:115], v[124:125], v[154:155] op_sel_hi:[0,1,1]
	v_pk_fma_f32 v[124:125], v[116:117], v[126:127], v[0:1] op_sel_hi:[1,1,0] neg_lo:[0,0,1] neg_hi:[0,0,1]
	v_mul_f32_e32 v0, v117, v126
	v_pk_fma_f32 v[126:127], v[116:117], v[126:127], v[0:1] op_sel:[0,1,0] op_sel_hi:[1,0,0]
	v_sub_f32_e32 v114, v120, v154
	v_sub_f32_e32 v118, v128, v144
	v_mov_b32_e32 v116, v124
	v_mov_b32_e32 v117, v126
	v_mov_b32_e32 v120, v150
	v_mov_b32_e32 v121, v152

.LBB0_752:
	s_and_saveexec_b64 s[28:29], s[10:11]
	s_cbranch_execz .LBB0_756
	s_mov_b32 s12, 0x2aaaaaab
	v_mul_hi_i32 v0, v138, s12
	v_lshrrev_b32_e32 v119, 31, v0
	v_lshrrev_b32_e32 v0, 4, v0
	v_add_u32_e32 v0, v0, v119
	s_movk_i32 s12, 0x60
	v_mul_lo_u32 v0, v0, s12
	v_sub_u32_e32 v119, v138, v0
	v_cmp_lt_i32_e64 s[12:13], 63, v119
	s_and_b64 s[12:13], s[12:13], s[8:9]
	s_and_saveexec_b64 s[30:31], s[12:13]
	s_cbranch_execz .LBB0_755
	v_and_b32_e32 v0, 0x7ffffff0, v119
	v_cmp_eq_u32_e64 s[12:13], 64, v0
	s_nop 1
	v_cndmask_b32_e64 v0, v118, v141, s[12:13]
	v_lshlrev_b32_e32 v0, 6, v0
	v_add_u32_e32 v120, 0x20000, v0
	v_lshlrev_b32_e32 v0, 2, v119
	v_and_b32_e32 v0, 32, v0
	v_add_u32_e32 v120, v120, v0
	ds_read2_b64 v[124:127], v120 offset0:2 offset1:3
	ds_read2_b64 v[142:145], v120 offset1:1
	s_waitcnt lgkmcnt(0)
	v_pk_mul_f32 v[150:151], v[106:107], v[124:125] op_sel:[1,1] op_sel_hi:[1,0]
	v_pk_mul_f32 v[128:129], v[110:111], v[142:143] op_sel:[1,1] op_sel_hi:[1,0]
	v_mul_f32_e32 v0, v113, v145
	v_pk_mul_f32 v[120:121], v[110:111], v[142:143]
	v_pk_fma_f32 v[110:111], v[110:111], v[142:143], v[128:129] op_sel_hi:[0,1,1]
	v_pk_fma_f32 v[142:143], v[112:113], v[144:145], v[0:1] op_sel_hi:[1,1,0] neg_lo:[0,0,1] neg_hi:[0,0,1]
	v_mul_f32_e32 v0, v113, v144
	v_pk_fma_f32 v[144:145], v[112:113], v[144:145], v[0:1] op_sel:[0,1,0] op_sel_hi:[1,0,0]
	v_mul_f32_e32 v0, v109, v127
	v_pk_mul_f32 v[112:113], v[106:107], v[124:125]
	v_pk_fma_f32 v[106:107], v[106:107], v[124:125], v[150:151] op_sel_hi:[0,1,1]
	v_pk_fma_f32 v[124:125], v[108:109], v[126:127], v[0:1] op_sel_hi:[1,1,0] neg_lo:[0,0,1] neg_hi:[0,0,1]
	v_mul_f32_e32 v0, v109, v126
	v_pk_fma_f32 v[126:127], v[108:109], v[126:127], v[0:1] op_sel:[0,1,0] op_sel_hi:[1,0,0]
	v_sub_f32_e32 v106, v112, v150
	v_sub_f32_e32 v110, v120, v128
	v_mov_b32_e32 v108, v124
	v_mov_b32_e32 v109, v126
	v_mov_b32_e32 v112, v142
	v_mov_b32_e32 v113, v144

.LBB0_760:
	s_and_saveexec_b64 s[26:27], s[10:11]
	s_cbranch_execz .LBB0_764
	s_mov_b32 s10, 0x2aaaaaab
	v_mul_hi_i32 v0, v122, s10
	v_lshrrev_b32_e32 v106, 31, v0
	v_lshrrev_b32_e32 v0, 4, v0
	v_add_u32_e32 v0, v0, v106
	s_movk_i32 s10, 0x60
	v_mul_lo_u32 v0, v0, s10
	v_sub_u32_e32 v106, v122, v0
	v_cmp_lt_i32_e64 s[10:11], 63, v106
	s_and_b64 s[8:9], s[8:9], s[10:11]
	s_and_saveexec_b64 s[10:11], s[8:9]
	s_cbranch_execz .LBB0_763
	v_and_b32_e32 v0, 0x7ffffff0, v106
	v_cmp_eq_u32_e64 s[8:9], 64, v0
	s_nop 1
	v_cndmask_b32_e64 v0, v118, v141, s[8:9]
	v_lshlrev_b32_e32 v0, 6, v0
	v_add_u32_e32 v108, 0x20000, v0
	v_lshlrev_b32_e32 v0, 2, v106
	v_and_b32_e32 v0, 56, v0
	v_add_u32_e32 v110, v108, v0
	ds_read2_b64 v[106:109], v110 offset0:2 offset1:3
	ds_read2_b64 v[110:113], v110 offset1:1
	s_waitcnt lgkmcnt(0)
	v_pk_mul_f32 v[124:125], v[98:99], v[106:107] op_sel:[1,1] op_sel_hi:[1,0]
	v_pk_mul_f32 v[120:121], v[102:103], v[110:111] op_sel:[1,1] op_sel_hi:[1,0]
	v_mul_f32_e32 v0, v105, v113
	v_pk_mul_f32 v[116:117], v[102:103], v[110:111]
	v_pk_fma_f32 v[102:103], v[102:103], v[110:111], v[120:121] op_sel_hi:[0,1,1]
	v_pk_fma_f32 v[110:111], v[104:105], v[112:113], v[0:1] op_sel_hi:[1,1,0] neg_lo:[0,0,1] neg_hi:[0,0,1]
	v_mul_f32_e32 v0, v105, v112
	v_pk_fma_f32 v[112:113], v[104:105], v[112:113], v[0:1] op_sel:[0,1,0] op_sel_hi:[1,0,0]
	v_mul_f32_e32 v0, v101, v109
	v_pk_mul_f32 v[104:105], v[98:99], v[106:107]
	v_pk_fma_f32 v[98:99], v[98:99], v[106:107], v[124:125] op_sel_hi:[0,1,1]
	v_pk_fma_f32 v[106:107], v[100:101], v[108:109], v[0:1] op_sel_hi:[1,1,0] neg_lo:[0,0,1] neg_hi:[0,0,1]
	v_mul_f32_e32 v0, v101, v108
	v_pk_fma_f32 v[108:109], v[100:101], v[108:109], v[0:1] op_sel:[0,1,0] op_sel_hi:[1,0,0]
	v_sub_f32_e32 v98, v104, v124
	v_sub_f32_e32 v102, v116, v120
	v_mov_b32_e32 v100, v106
	v_mov_b32_e32 v101, v108
	v_mov_b32_e32 v104, v110
	v_mov_b32_e32 v105, v112

.LBB0_772:
	s_and_saveexec_b64 s[28:29], s[10:11]
	s_cbranch_execz .LBB0_776
	s_mov_b32 s12, 0x2aaaaaab
	v_mul_hi_i32 v0, v138, s12
	v_lshrrev_b32_e32 v103, 31, v0
	v_lshrrev_b32_e32 v0, 4, v0
	v_add_u32_e32 v0, v0, v103
	s_movk_i32 s12, 0x60
	v_mul_lo_u32 v0, v0, s12
	v_sub_u32_e32 v103, v138, v0
	v_cmp_lt_i32_e64 s[12:13], 63, v103
	s_and_b64 s[12:13], s[12:13], s[8:9]
	s_and_saveexec_b64 s[30:31], s[12:13]
	s_cbranch_execz .LBB0_775
	v_and_b32_e32 v0, 0x7ffffff0, v103
	v_cmp_eq_u32_e64 s[12:13], 64, v0
	s_nop 1
	v_cndmask_b32_e64 v0, v102, v141, s[12:13]
	v_lshlrev_b32_e32 v0, 6, v0
	v_add_u32_e32 v104, 0x20000, v0
	v_lshlrev_b32_e32 v0, 2, v103
	v_and_b32_e32 v0, 32, v0
	v_add_u32_e32 v108, v104, v0
	ds_read2_b64 v[104:107], v108 offset0:2 offset1:3
	ds_read2_b64 v[108:111], v108 offset1:1
	s_waitcnt lgkmcnt(0)
	v_pk_mul_f32 v[116:117], v[90:91], v[104:105] op_sel:[1,1] op_sel_hi:[1,0]
	v_pk_mul_f32 v[114:115], v[94:95], v[108:109] op_sel:[1,1] op_sel_hi:[1,0]
	v_mul_f32_e32 v0, v97, v111
	v_pk_mul_f32 v[112:113], v[94:95], v[108:109]
	v_pk_fma_f32 v[94:95], v[94:95], v[108:109], v[114:115] op_sel_hi:[0,1,1]
	v_pk_fma_f32 v[108:109], v[96:97], v[110:111], v[0:1] op_sel_hi:[1,1,0] neg_lo:[0,0,1] neg_hi:[0,0,1]
	v_mul_f32_e32 v0, v97, v110
	v_pk_fma_f32 v[110:111], v[96:97], v[110:111], v[0:1] op_sel:[0,1,0] op_sel_hi:[1,0,0]
	v_mul_f32_e32 v0, v93, v107
	v_pk_mul_f32 v[96:97], v[90:91], v[104:105]
	v_pk_fma_f32 v[90:91], v[90:91], v[104:105], v[116:117] op_sel_hi:[0,1,1]
	v_pk_fma_f32 v[104:105], v[92:93], v[106:107], v[0:1] op_sel_hi:[1,1,0] neg_lo:[0,0,1] neg_hi:[0,0,1]
	v_mul_f32_e32 v0, v93, v106
	v_pk_fma_f32 v[106:107], v[92:93], v[106:107], v[0:1] op_sel:[0,1,0] op_sel_hi:[1,0,0]
	v_sub_f32_e32 v90, v96, v116
	v_sub_f32_e32 v94, v112, v114
	v_mov_b32_e32 v92, v104
	v_mov_b32_e32 v93, v106
	v_mov_b32_e32 v96, v108
	v_mov_b32_e32 v97, v110

.LBB0_780:
	s_and_saveexec_b64 s[26:27], s[10:11]
	s_cbranch_execz .LBB0_784
	s_mov_b32 s10, 0x2aaaaaab
	v_mul_hi_i32 v0, v122, s10
	v_lshrrev_b32_e32 v90, 31, v0
	v_lshrrev_b32_e32 v0, 4, v0
	v_add_u32_e32 v0, v0, v90
	s_movk_i32 s10, 0x60
	v_mul_lo_u32 v0, v0, s10
	v_sub_u32_e32 v90, v122, v0
	v_cmp_lt_i32_e64 s[10:11], 63, v90
	s_and_b64 s[8:9], s[8:9], s[10:11]
	s_and_saveexec_b64 s[10:11], s[8:9]
	s_cbranch_execz .LBB0_783
	v_and_b32_e32 v0, 0x7ffffff0, v90
	v_cmp_eq_u32_e64 s[8:9], 64, v0
	s_nop 1
	v_cndmask_b32_e64 v0, v102, v141, s[8:9]
	v_lshlrev_b32_e32 v0, 6, v0
	v_add_u32_e32 v92, 0x20000, v0
	v_lshlrev_b32_e32 v0, 2, v90
	v_and_b32_e32 v0, 56, v0
	v_add_u32_e32 v94, v92, v0
	ds_read2_b64 v[90:93], v94 offset0:2 offset1:3
	ds_read2_b64 v[94:97], v94 offset1:1
	s_waitcnt lgkmcnt(0)
	v_pk_mul_f32 v[106:107], v[82:83], v[90:91] op_sel:[1,1] op_sel_hi:[1,0]
	v_pk_mul_f32 v[104:105], v[86:87], v[94:95] op_sel:[1,1] op_sel_hi:[1,0]
	v_mul_f32_e32 v0, v89, v97
	v_pk_mul_f32 v[100:101], v[86:87], v[94:95]
	v_pk_fma_f32 v[86:87], v[86:87], v[94:95], v[104:105] op_sel_hi:[0,1,1]
	v_pk_fma_f32 v[94:95], v[88:89], v[96:97], v[0:1] op_sel_hi:[1,1,0] neg_lo:[0,0,1] neg_hi:[0,0,1]
	v_mul_f32_e32 v0, v89, v96
	v_pk_fma_f32 v[96:97], v[88:89], v[96:97], v[0:1] op_sel:[0,1,0] op_sel_hi:[1,0,0]
	v_mul_f32_e32 v0, v85, v93
	v_pk_mul_f32 v[88:89], v[82:83], v[90:91]
	v_pk_fma_f32 v[82:83], v[82:83], v[90:91], v[106:107] op_sel_hi:[0,1,1]
	v_pk_fma_f32 v[90:91], v[84:85], v[92:93], v[0:1] op_sel_hi:[1,1,0] neg_lo:[0,0,1] neg_hi:[0,0,1]
	v_mul_f32_e32 v0, v85, v92
	v_pk_fma_f32 v[92:93], v[84:85], v[92:93], v[0:1] op_sel:[0,1,0] op_sel_hi:[1,0,0]
	v_sub_f32_e32 v82, v88, v106
	v_sub_f32_e32 v86, v100, v104
	v_mov_b32_e32 v84, v90
	v_mov_b32_e32 v85, v92
	v_mov_b32_e32 v88, v94
	v_mov_b32_e32 v89, v96

.LBB0_792:
	s_and_saveexec_b64 s[28:29], s[10:11]
	s_cbranch_execz .LBB0_796
	s_mov_b32 s12, 0x2aaaaaab
	v_mul_hi_i32 v0, v138, s12
	v_lshrrev_b32_e32 v87, 31, v0
	v_lshrrev_b32_e32 v0, 4, v0
	v_add_u32_e32 v0, v0, v87
	s_movk_i32 s12, 0x60
	v_mul_lo_u32 v0, v0, s12
	v_sub_u32_e32 v87, v138, v0
	v_cmp_lt_i32_e64 s[12:13], 63, v87
	s_and_b64 s[12:13], s[12:13], s[8:9]
	s_and_saveexec_b64 s[30:31], s[12:13]
	s_cbranch_execz .LBB0_795
	v_and_b32_e32 v0, 0x7ffffff0, v87
	v_cmp_eq_u32_e64 s[12:13], 64, v0
	s_nop 1
	v_cndmask_b32_e64 v0, v86, v141, s[12:13]
	v_lshlrev_b32_e32 v0, 6, v0
	v_add_u32_e32 v88, 0x20000, v0
	v_lshlrev_b32_e32 v0, 2, v87
	v_and_b32_e32 v0, 32, v0
	v_add_u32_e32 v92, v88, v0
	ds_read2_b64 v[88:91], v92 offset0:2 offset1:3
	ds_read2_b64 v[92:95], v92 offset1:1
	s_waitcnt lgkmcnt(0)
	v_pk_mul_f32 v[100:101], v[74:75], v[88:89] op_sel:[1,1] op_sel_hi:[1,0]
	v_pk_mul_f32 v[98:99], v[78:79], v[92:93] op_sel:[1,1] op_sel_hi:[1,0]
	v_mul_f32_e32 v0, v81, v95
	v_pk_mul_f32 v[96:97], v[78:79], v[92:93]
	v_pk_fma_f32 v[78:79], v[78:79], v[92:93], v[98:99] op_sel_hi:[0,1,1]
	v_pk_fma_f32 v[92:93], v[80:81], v[94:95], v[0:1] op_sel_hi:[1,1,0] neg_lo:[0,0,1] neg_hi:[0,0,1]
	v_mul_f32_e32 v0, v81, v94
	v_pk_fma_f32 v[94:95], v[80:81], v[94:95], v[0:1] op_sel:[0,1,0] op_sel_hi:[1,0,0]
	v_mul_f32_e32 v0, v77, v91
	v_pk_mul_f32 v[80:81], v[74:75], v[88:89]
	v_pk_fma_f32 v[74:75], v[74:75], v[88:89], v[100:101] op_sel_hi:[0,1,1]
	v_pk_fma_f32 v[88:89], v[76:77], v[90:91], v[0:1] op_sel_hi:[1,1,0] neg_lo:[0,0,1] neg_hi:[0,0,1]
	v_mul_f32_e32 v0, v77, v90
	v_pk_fma_f32 v[90:91], v[76:77], v[90:91], v[0:1] op_sel:[0,1,0] op_sel_hi:[1,0,0]
	v_sub_f32_e32 v74, v80, v100
	v_sub_f32_e32 v78, v96, v98
	v_mov_b32_e32 v76, v88
	v_mov_b32_e32 v77, v90
	v_mov_b32_e32 v80, v92
	v_mov_b32_e32 v81, v94

.LBB0_800:
	s_and_saveexec_b64 s[26:27], s[10:11]
	s_cbranch_execz .LBB0_804
	s_mov_b32 s10, 0x2aaaaaab
	v_mul_hi_i32 v0, v122, s10
	v_lshrrev_b32_e32 v74, 31, v0
	v_lshrrev_b32_e32 v0, 4, v0
	v_add_u32_e32 v0, v0, v74
	s_movk_i32 s10, 0x60
	v_mul_lo_u32 v0, v0, s10
	v_sub_u32_e32 v74, v122, v0
	v_cmp_lt_i32_e64 s[10:11], 63, v74
	s_and_b64 s[8:9], s[8:9], s[10:11]
	s_and_saveexec_b64 s[10:11], s[8:9]
	s_cbranch_execz .LBB0_803
	v_and_b32_e32 v0, 0x7ffffff0, v74
	v_cmp_eq_u32_e64 s[8:9], 64, v0
	s_nop 1
	v_cndmask_b32_e64 v0, v86, v141, s[8:9]
	v_lshlrev_b32_e32 v0, 6, v0
	v_add_u32_e32 v76, 0x20000, v0
	v_lshlrev_b32_e32 v0, 2, v74
	v_and_b32_e32 v0, 56, v0
	v_add_u32_e32 v78, v76, v0
	ds_read2_b64 v[74:77], v78 offset0:2 offset1:3
	ds_read2_b64 v[78:81], v78 offset1:1
	s_waitcnt lgkmcnt(0)
	v_pk_mul_f32 v[90:91], v[66:67], v[74:75] op_sel:[1,1] op_sel_hi:[1,0]
	v_pk_mul_f32 v[88:89], v[70:71], v[78:79] op_sel:[1,1] op_sel_hi:[1,0]
	v_mul_f32_e32 v0, v73, v81
	v_pk_mul_f32 v[84:85], v[70:71], v[78:79]
	v_pk_fma_f32 v[70:71], v[70:71], v[78:79], v[88:89] op_sel_hi:[0,1,1]
	v_pk_fma_f32 v[78:79], v[72:73], v[80:81], v[0:1] op_sel_hi:[1,1,0] neg_lo:[0,0,1] neg_hi:[0,0,1]
	v_mul_f32_e32 v0, v73, v80
	v_pk_fma_f32 v[80:81], v[72:73], v[80:81], v[0:1] op_sel:[0,1,0] op_sel_hi:[1,0,0]
	v_mul_f32_e32 v0, v69, v77
	v_pk_mul_f32 v[72:73], v[66:67], v[74:75]
	v_pk_fma_f32 v[66:67], v[66:67], v[74:75], v[90:91] op_sel_hi:[0,1,1]
	v_pk_fma_f32 v[74:75], v[68:69], v[76:77], v[0:1] op_sel_hi:[1,1,0] neg_lo:[0,0,1] neg_hi:[0,0,1]
	v_mul_f32_e32 v0, v69, v76
	v_pk_fma_f32 v[76:77], v[68:69], v[76:77], v[0:1] op_sel:[0,1,0] op_sel_hi:[1,0,0]
	v_sub_f32_e32 v66, v72, v90
	v_sub_f32_e32 v70, v84, v88
	v_mov_b32_e32 v68, v74
	v_mov_b32_e32 v69, v76
	v_mov_b32_e32 v72, v78
	v_mov_b32_e32 v73, v80

.LBB0_812:
	s_and_saveexec_b64 s[28:29], s[10:11]
	s_cbranch_execz .LBB0_816
	s_mov_b32 s12, 0x2aaaaaab
	v_mul_hi_i32 v0, v138, s12
	v_lshrrev_b32_e32 v71, 31, v0
	v_lshrrev_b32_e32 v0, 4, v0
	v_add_u32_e32 v0, v0, v71
	s_movk_i32 s12, 0x60
	v_mul_lo_u32 v0, v0, s12
	v_sub_u32_e32 v71, v138, v0
	v_cmp_lt_i32_e64 s[12:13], 63, v71
	s_and_b64 s[12:13], s[8:9], s[12:13]
	s_and_saveexec_b64 s[30:31], s[12:13]
	s_cbranch_execz .LBB0_815
	v_and_b32_e32 v0, 0x7ffffff0, v71
	v_cmp_eq_u32_e64 s[12:13], 64, v0
	s_nop 1
	v_cndmask_b32_e64 v0, v149, v70, s[12:13]
	v_lshlrev_b32_e32 v0, 6, v0
	v_add_u32_e32 v72, 0x20000, v0
	v_lshlrev_b32_e32 v0, 2, v71
	v_and_b32_e32 v0, 32, v0
	v_add_u32_e32 v76, v72, v0
	ds_read2_b64 v[72:75], v76 offset0:2 offset1:3
	ds_read2_b64 v[76:79], v76 offset1:1
	s_waitcnt lgkmcnt(0)
	v_pk_mul_f32 v[84:85], v[58:59], v[72:73] op_sel:[1,1] op_sel_hi:[1,0]
	v_pk_mul_f32 v[82:83], v[62:63], v[76:77] op_sel:[1,1] op_sel_hi:[1,0]
	v_mul_f32_e32 v0, v65, v79
	v_pk_mul_f32 v[80:81], v[62:63], v[76:77]
	v_pk_fma_f32 v[62:63], v[62:63], v[76:77], v[82:83] op_sel_hi:[0,1,1]
	v_pk_fma_f32 v[76:77], v[64:65], v[78:79], v[0:1] op_sel_hi:[1,1,0] neg_lo:[0,0,1] neg_hi:[0,0,1]
	v_mul_f32_e32 v0, v65, v78
	v_pk_fma_f32 v[78:79], v[64:65], v[78:79], v[0:1] op_sel:[0,1,0] op_sel_hi:[1,0,0]
	v_mul_f32_e32 v0, v61, v75
	v_pk_mul_f32 v[64:65], v[58:59], v[72:73]
	v_pk_fma_f32 v[58:59], v[58:59], v[72:73], v[84:85] op_sel_hi:[0,1,1]
	v_pk_fma_f32 v[72:73], v[60:61], v[74:75], v[0:1] op_sel_hi:[1,1,0] neg_lo:[0,0,1] neg_hi:[0,0,1]
	v_mul_f32_e32 v0, v61, v74
	v_pk_fma_f32 v[74:75], v[60:61], v[74:75], v[0:1] op_sel:[0,1,0] op_sel_hi:[1,0,0]
	v_sub_f32_e32 v58, v64, v84
	v_sub_f32_e32 v62, v80, v82
	v_mov_b32_e32 v60, v72
	v_mov_b32_e32 v61, v74
	v_mov_b32_e32 v64, v76
	v_mov_b32_e32 v65, v78

.LBB0_820:
	s_and_saveexec_b64 s[26:27], s[10:11]
	s_cbranch_execz .LBB0_824
	s_mov_b32 s10, 0x2aaaaaab
	v_mul_hi_i32 v0, v122, s10
	v_lshrrev_b32_e32 v58, 31, v0
	v_lshrrev_b32_e32 v0, 4, v0
	v_add_u32_e32 v0, v0, v58
	s_movk_i32 s10, 0x60
	v_mul_lo_u32 v0, v0, s10
	v_sub_u32_e32 v58, v122, v0
	v_cmp_lt_i32_e64 s[10:11], 63, v58
	s_and_b64 s[8:9], s[8:9], s[10:11]
	s_and_saveexec_b64 s[10:11], s[8:9]
	s_cbranch_execz .LBB0_823
	v_and_b32_e32 v0, 0x7ffffff0, v58
	v_cmp_eq_u32_e64 s[8:9], 64, v0
	s_nop 1
	v_cndmask_b32_e64 v0, v149, v70, s[8:9]
	v_lshlrev_b32_e32 v0, 6, v0
	v_add_u32_e32 v60, 0x20000, v0
	v_lshlrev_b32_e32 v0, 2, v58
	v_and_b32_e32 v0, 56, v0
	v_add_u32_e32 v62, v60, v0
	ds_read2_b64 v[58:61], v62 offset0:2 offset1:3
	ds_read2_b64 v[62:65], v62 offset1:1
	s_waitcnt lgkmcnt(0)
	v_pk_mul_f32 v[74:75], v[50:51], v[58:59] op_sel:[1,1] op_sel_hi:[1,0]
	v_pk_mul_f32 v[72:73], v[54:55], v[62:63] op_sel:[1,1] op_sel_hi:[1,0]
	v_mul_f32_e32 v0, v57, v65
	v_pk_mul_f32 v[68:69], v[54:55], v[62:63]
	v_pk_fma_f32 v[54:55], v[54:55], v[62:63], v[72:73] op_sel_hi:[0,1,1]
	v_pk_fma_f32 v[62:63], v[56:57], v[64:65], v[0:1] op_sel_hi:[1,1,0] neg_lo:[0,0,1] neg_hi:[0,0,1]
	v_mul_f32_e32 v0, v57, v64
	v_pk_fma_f32 v[64:65], v[56:57], v[64:65], v[0:1] op_sel:[0,1,0] op_sel_hi:[1,0,0]
	v_mul_f32_e32 v0, v53, v61
	v_pk_mul_f32 v[56:57], v[50:51], v[58:59]
	v_pk_fma_f32 v[50:51], v[50:51], v[58:59], v[74:75] op_sel_hi:[0,1,1]
	v_pk_fma_f32 v[58:59], v[52:53], v[60:61], v[0:1] op_sel_hi:[1,1,0] neg_lo:[0,0,1] neg_hi:[0,0,1]
	v_mul_f32_e32 v0, v53, v60
	v_pk_fma_f32 v[60:61], v[52:53], v[60:61], v[0:1] op_sel:[0,1,0] op_sel_hi:[1,0,0]
	v_sub_f32_e32 v50, v56, v74
	v_sub_f32_e32 v54, v68, v72
	v_mov_b32_e32 v52, v58
	v_mov_b32_e32 v53, v60
	v_mov_b32_e32 v56, v62
	v_mov_b32_e32 v57, v64

.LBB0_832:
	s_and_saveexec_b64 s[28:29], s[10:11]
	s_cbranch_execz .LBB0_836
	s_mov_b32 s12, 0x2aaaaaab
	v_mul_hi_i32 v0, v138, s12
	v_lshrrev_b32_e32 v54, 31, v0
	v_lshrrev_b32_e32 v0, 4, v0
	v_add_u32_e32 v0, v0, v54
	s_movk_i32 s12, 0x60
	v_mul_lo_u32 v0, v0, s12
	v_sub_u32_e32 v54, v138, v0
	v_cmp_lt_i32_e64 s[12:13], 63, v54
	s_and_b64 s[12:13], s[8:9], s[12:13]
	s_and_saveexec_b64 s[30:31], s[12:13]
	s_cbranch_execz .LBB0_835
	v_and_b32_e32 v0, 0x7ffffff0, v54
	v_cmp_eq_u32_e64 s[12:13], 64, v0
	s_nop 1
	v_cndmask_b32_e64 v0, v118, v70, s[12:13]
	v_lshlrev_b32_e32 v0, 6, v0
	v_add_u32_e32 v56, 0x20000, v0
	v_lshlrev_b32_e32 v0, 2, v54
	v_and_b32_e32 v0, 32, v0
	v_add_u32_e32 v58, v56, v0
	ds_read2_b64 v[54:57], v58 offset0:2 offset1:3
	ds_read2_b64 v[58:61], v58 offset1:1
	s_waitcnt lgkmcnt(0)
	v_pk_mul_f32 v[66:67], v[42:43], v[54:55] op_sel:[1,1] op_sel_hi:[1,0]
	v_pk_mul_f32 v[64:65], v[46:47], v[58:59] op_sel:[1,1] op_sel_hi:[1,0]
	v_mul_f32_e32 v0, v49, v61
	v_pk_mul_f32 v[62:63], v[46:47], v[58:59]
	v_pk_fma_f32 v[46:47], v[46:47], v[58:59], v[64:65] op_sel_hi:[0,1,1]
	v_pk_fma_f32 v[58:59], v[48:49], v[60:61], v[0:1] op_sel_hi:[1,1,0] neg_lo:[0,0,1] neg_hi:[0,0,1]
	v_mul_f32_e32 v0, v49, v60
	v_pk_fma_f32 v[60:61], v[48:49], v[60:61], v[0:1] op_sel:[0,1,0] op_sel_hi:[1,0,0]
	v_mul_f32_e32 v0, v45, v57
	v_pk_mul_f32 v[48:49], v[42:43], v[54:55]
	v_pk_fma_f32 v[42:43], v[42:43], v[54:55], v[66:67] op_sel_hi:[0,1,1]
	v_pk_fma_f32 v[54:55], v[44:45], v[56:57], v[0:1] op_sel_hi:[1,1,0] neg_lo:[0,0,1] neg_hi:[0,0,1]
	v_mul_f32_e32 v0, v45, v56
	v_pk_fma_f32 v[56:57], v[44:45], v[56:57], v[0:1] op_sel:[0,1,0] op_sel_hi:[1,0,0]
	v_sub_f32_e32 v42, v48, v66
	v_sub_f32_e32 v46, v62, v64
	v_mov_b32_e32 v44, v54
	v_mov_b32_e32 v45, v56
	v_mov_b32_e32 v48, v58
	v_mov_b32_e32 v49, v60

.LBB0_840:
	s_and_saveexec_b64 s[26:27], s[10:11]
	s_cbranch_execz .LBB0_844
	s_mov_b32 s10, 0x2aaaaaab
	v_mul_hi_i32 v0, v122, s10
	v_lshrrev_b32_e32 v42, 31, v0
	v_lshrrev_b32_e32 v0, 4, v0
	v_add_u32_e32 v0, v0, v42
	s_movk_i32 s10, 0x60
	v_mul_lo_u32 v0, v0, s10
	v_sub_u32_e32 v42, v122, v0
	v_cmp_lt_i32_e64 s[10:11], 63, v42
	s_and_b64 s[8:9], s[8:9], s[10:11]
	s_and_saveexec_b64 s[10:11], s[8:9]
	s_cbranch_execz .LBB0_843
	v_and_b32_e32 v0, 0x7ffffff0, v42
	v_cmp_eq_u32_e64 s[8:9], 64, v0
	s_nop 1
	v_cndmask_b32_e64 v0, v118, v70, s[8:9]
	v_lshlrev_b32_e32 v0, 6, v0
	v_add_u32_e32 v44, 0x20000, v0
	v_lshlrev_b32_e32 v0, 2, v42
	v_and_b32_e32 v0, 56, v0
	v_add_u32_e32 v46, v44, v0
	ds_read2_b64 v[42:45], v46 offset0:2 offset1:3
	ds_read2_b64 v[46:49], v46 offset1:1
	s_waitcnt lgkmcnt(0)
	v_pk_mul_f32 v[56:57], v[34:35], v[42:43] op_sel:[1,1] op_sel_hi:[1,0]
	v_pk_mul_f32 v[54:55], v[38:39], v[46:47] op_sel:[1,1] op_sel_hi:[1,0]
	v_mul_f32_e32 v0, v41, v49
	v_pk_mul_f32 v[52:53], v[38:39], v[46:47]
	v_pk_fma_f32 v[38:39], v[38:39], v[46:47], v[54:55] op_sel_hi:[0,1,1]
	v_pk_fma_f32 v[46:47], v[40:41], v[48:49], v[0:1] op_sel_hi:[1,1,0] neg_lo:[0,0,1] neg_hi:[0,0,1]
	v_mul_f32_e32 v0, v41, v48
	v_pk_fma_f32 v[48:49], v[40:41], v[48:49], v[0:1] op_sel:[0,1,0] op_sel_hi:[1,0,0]
	v_mul_f32_e32 v0, v37, v45
	v_pk_mul_f32 v[40:41], v[34:35], v[42:43]
	v_pk_fma_f32 v[34:35], v[34:35], v[42:43], v[56:57] op_sel_hi:[0,1,1]
	v_pk_fma_f32 v[42:43], v[36:37], v[44:45], v[0:1] op_sel_hi:[1,1,0] neg_lo:[0,0,1] neg_hi:[0,0,1]
	v_mul_f32_e32 v0, v37, v44
	v_pk_fma_f32 v[44:45], v[36:37], v[44:45], v[0:1] op_sel:[0,1,0] op_sel_hi:[1,0,0]
	v_sub_f32_e32 v34, v40, v56
	v_sub_f32_e32 v38, v52, v54
	v_mov_b32_e32 v36, v42
	v_mov_b32_e32 v37, v44
	v_mov_b32_e32 v40, v46
	v_mov_b32_e32 v41, v48

.LBB0_852:
	s_and_saveexec_b64 s[28:29], s[10:11]
	s_cbranch_execz .LBB0_856
	s_mov_b32 s12, 0x2aaaaaab
	v_mul_hi_i32 v0, v138, s12
	v_lshrrev_b32_e32 v38, 31, v0
	v_lshrrev_b32_e32 v0, 4, v0
	v_add_u32_e32 v0, v0, v38
	s_movk_i32 s12, 0x60
	v_mul_lo_u32 v0, v0, s12
	v_sub_u32_e32 v38, v138, v0
	v_cmp_lt_i32_e64 s[12:13], 63, v38
	s_and_b64 s[12:13], s[8:9], s[12:13]
	s_and_saveexec_b64 s[30:31], s[12:13]
	s_cbranch_execz .LBB0_855
	v_and_b32_e32 v0, 0x7ffffff0, v38
	v_cmp_eq_u32_e64 s[12:13], 64, v0
	s_nop 1
	v_cndmask_b32_e64 v0, v102, v70, s[12:13]
	v_lshlrev_b32_e32 v0, 6, v0
	v_add_u32_e32 v40, 0x20000, v0
	v_lshlrev_b32_e32 v0, 2, v38
	v_and_b32_e32 v0, 32, v0
	v_add_u32_e32 v42, v40, v0
	ds_read2_b64 v[38:41], v42 offset0:2 offset1:3
	ds_read2_b64 v[42:45], v42 offset1:1
	s_waitcnt lgkmcnt(0)
	v_pk_mul_f32 v[50:51], v[26:27], v[38:39] op_sel:[1,1] op_sel_hi:[1,0]
	v_pk_mul_f32 v[48:49], v[30:31], v[42:43] op_sel:[1,1] op_sel_hi:[1,0]
	v_mul_f32_e32 v0, v33, v45
	v_pk_mul_f32 v[46:47], v[30:31], v[42:43]
	v_pk_fma_f32 v[30:31], v[30:31], v[42:43], v[48:49] op_sel_hi:[0,1,1]
	v_pk_fma_f32 v[42:43], v[32:33], v[44:45], v[0:1] op_sel_hi:[1,1,0] neg_lo:[0,0,1] neg_hi:[0,0,1]
	v_mul_f32_e32 v0, v33, v44
	v_pk_fma_f32 v[44:45], v[32:33], v[44:45], v[0:1] op_sel:[0,1,0] op_sel_hi:[1,0,0]
	v_mul_f32_e32 v0, v29, v41
	v_pk_mul_f32 v[32:33], v[26:27], v[38:39]
	v_pk_fma_f32 v[26:27], v[26:27], v[38:39], v[50:51] op_sel_hi:[0,1,1]
	v_pk_fma_f32 v[38:39], v[28:29], v[40:41], v[0:1] op_sel_hi:[1,1,0] neg_lo:[0,0,1] neg_hi:[0,0,1]
	v_mul_f32_e32 v0, v29, v40
	v_pk_fma_f32 v[40:41], v[28:29], v[40:41], v[0:1] op_sel:[0,1,0] op_sel_hi:[1,0,0]
	v_sub_f32_e32 v26, v32, v50
	v_sub_f32_e32 v30, v46, v48
	v_mov_b32_e32 v28, v38
	v_mov_b32_e32 v29, v40
	v_mov_b32_e32 v32, v42
	v_mov_b32_e32 v33, v44

.LBB0_860:
	s_and_saveexec_b64 s[26:27], s[10:11]
	s_cbranch_execz .LBB0_864
	s_mov_b32 s10, 0x2aaaaaab
	v_mul_hi_i32 v0, v122, s10
	v_lshrrev_b32_e32 v26, 31, v0
	v_lshrrev_b32_e32 v0, 4, v0
	v_add_u32_e32 v0, v0, v26
	s_movk_i32 s10, 0x60
	v_mul_lo_u32 v0, v0, s10
	v_sub_u32_e32 v26, v122, v0
	v_cmp_lt_i32_e64 s[10:11], 63, v26
	s_and_b64 s[8:9], s[8:9], s[10:11]
	s_and_saveexec_b64 s[10:11], s[8:9]
	s_cbranch_execz .LBB0_863
	v_and_b32_e32 v0, 0x7ffffff0, v26
	v_cmp_eq_u32_e64 s[8:9], 64, v0
	s_nop 1
	v_cndmask_b32_e64 v0, v102, v70, s[8:9]
	v_lshlrev_b32_e32 v0, 6, v0
	v_add_u32_e32 v28, 0x20000, v0
	v_lshlrev_b32_e32 v0, 2, v26
	v_and_b32_e32 v0, 56, v0
	v_add_u32_e32 v30, v28, v0
	ds_read2_b64 v[26:29], v30 offset0:2 offset1:3
	ds_read2_b64 v[30:33], v30 offset1:1
	s_waitcnt lgkmcnt(0)
	v_pk_mul_f32 v[40:41], v[18:19], v[26:27] op_sel:[1,1] op_sel_hi:[1,0]
	v_pk_mul_f32 v[38:39], v[22:23], v[30:31] op_sel:[1,1] op_sel_hi:[1,0]
	v_mul_f32_e32 v0, v25, v33
	v_pk_mul_f32 v[36:37], v[22:23], v[30:31]
	v_pk_fma_f32 v[22:23], v[22:23], v[30:31], v[38:39] op_sel_hi:[0,1,1]
	v_pk_fma_f32 v[30:31], v[24:25], v[32:33], v[0:1] op_sel_hi:[1,1,0] neg_lo:[0,0,1] neg_hi:[0,0,1]
	v_mul_f32_e32 v0, v25, v32
	v_pk_fma_f32 v[32:33], v[24:25], v[32:33], v[0:1] op_sel:[0,1,0] op_sel_hi:[1,0,0]
	v_mul_f32_e32 v0, v21, v29
	v_pk_mul_f32 v[24:25], v[18:19], v[26:27]
	v_pk_fma_f32 v[18:19], v[18:19], v[26:27], v[40:41] op_sel_hi:[0,1,1]
	v_pk_fma_f32 v[26:27], v[20:21], v[28:29], v[0:1] op_sel_hi:[1,1,0] neg_lo:[0,0,1] neg_hi:[0,0,1]
	v_mul_f32_e32 v0, v21, v28
	v_pk_fma_f32 v[28:29], v[20:21], v[28:29], v[0:1] op_sel:[0,1,0] op_sel_hi:[1,0,0]
	v_sub_f32_e32 v18, v24, v40
	v_sub_f32_e32 v22, v36, v38
	v_mov_b32_e32 v20, v26
	v_mov_b32_e32 v21, v28
	v_mov_b32_e32 v24, v30
	v_mov_b32_e32 v25, v32

.LBB0_872:
	s_and_saveexec_b64 s[26:27], s[10:11]
	s_cbranch_execz .LBB0_876
	s_mov_b32 s6, 0x2aaaaaab
	v_mul_hi_i32 v0, v138, s6
	v_lshrrev_b32_e32 v22, 31, v0
	v_lshrrev_b32_e32 v0, 4, v0
	v_add_u32_e32 v0, v0, v22
	s_movk_i32 s6, 0x60
	v_mul_lo_u32 v0, v0, s6
	v_sub_u32_e32 v22, v138, v0
	v_cmp_lt_i32_e64 s[6:7], 63, v22
	s_and_b64 s[6:7], s[8:9], s[6:7]
	s_and_saveexec_b64 s[28:29], s[6:7]
	s_cbranch_execz .LBB0_875
	v_and_b32_e32 v0, 0x7ffffff0, v22
	v_cmp_eq_u32_e64 s[6:7], 64, v0
	s_nop 1
	v_cndmask_b32_e64 v0, v86, v70, s[6:7]
	v_lshlrev_b32_e32 v0, 6, v0
	v_add_u32_e32 v24, 0x20000, v0
	v_lshlrev_b32_e32 v0, 2, v22
	v_and_b32_e32 v0, 32, v0
	v_add_u32_e32 v26, v24, v0
	ds_read2_b64 v[22:25], v26 offset0:2 offset1:3
	ds_read2_b64 v[26:29], v26 offset1:1
	s_waitcnt lgkmcnt(0)
	v_pk_mul_f32 v[34:35], v[10:11], v[22:23] op_sel:[1,1] op_sel_hi:[1,0]
	v_pk_mul_f32 v[32:33], v[14:15], v[26:27] op_sel:[1,1] op_sel_hi:[1,0]
	v_mul_f32_e32 v0, v17, v29
	v_pk_mul_f32 v[30:31], v[14:15], v[26:27]
	v_pk_fma_f32 v[14:15], v[14:15], v[26:27], v[32:33] op_sel_hi:[0,1,1]
	v_pk_fma_f32 v[26:27], v[16:17], v[28:29], v[0:1] op_sel_hi:[1,1,0] neg_lo:[0,0,1] neg_hi:[0,0,1]
	v_mul_f32_e32 v0, v17, v28
	v_pk_fma_f32 v[28:29], v[16:17], v[28:29], v[0:1] op_sel:[0,1,0] op_sel_hi:[1,0,0]
	v_mul_f32_e32 v0, v13, v25
	v_pk_mul_f32 v[16:17], v[10:11], v[22:23]
	v_pk_fma_f32 v[10:11], v[10:11], v[22:23], v[34:35] op_sel_hi:[0,1,1]
	v_pk_fma_f32 v[22:23], v[12:13], v[24:25], v[0:1] op_sel_hi:[1,1,0] neg_lo:[0,0,1] neg_hi:[0,0,1]
	v_mul_f32_e32 v0, v13, v24
	v_pk_fma_f32 v[24:25], v[12:13], v[24:25], v[0:1] op_sel:[0,1,0] op_sel_hi:[1,0,0]
	v_sub_f32_e32 v10, v16, v34
	v_sub_f32_e32 v14, v30, v32
	v_mov_b32_e32 v12, v22
	v_mov_b32_e32 v13, v24
	v_mov_b32_e32 v16, v26
	v_mov_b32_e32 v17, v28

.LBB0_880:
	s_and_saveexec_b64 s[12:13], s[10:11]
	s_cbranch_execz .LBB0_715
	s_mov_b32 s10, 0x2aaaaaab
	v_mul_hi_i32 v0, v122, s10
	v_lshrrev_b32_e32 v10, 31, v0
	v_lshrrev_b32_e32 v0, 4, v0
	v_add_u32_e32 v0, v0, v10
	s_movk_i32 s10, 0x60
	v_mul_lo_u32 v0, v0, s10
	v_sub_u32_e32 v10, v122, v0
	v_cmp_lt_i32_e32 vcc, 63, v10
	s_and_b64 s[10:11], s[8:9], vcc
	s_and_saveexec_b64 s[8:9], s[10:11]
	s_cbranch_execz .LBB0_714
	v_and_b32_e32 v0, 0x7ffffff0, v10
	v_cmp_eq_u32_e32 vcc, 64, v0
	s_nop 1
	v_cndmask_b32_e32 v0, v86, v70, vcc
	v_lshlrev_b32_e32 v0, 6, v0
	v_add_u32_e32 v12, 0x20000, v0
	v_lshlrev_b32_e32 v0, 2, v10
	v_and_b32_e32 v0, 56, v0
	v_add_u32_e32 v14, v12, v0
	ds_read2_b64 v[10:13], v14 offset0:2 offset1:3
	ds_read2_b64 v[14:17], v14 offset1:1
	s_waitcnt lgkmcnt(0)
	v_pk_mul_f32 v[24:25], v[2:3], v[10:11] op_sel:[1,1] op_sel_hi:[1,0]
	v_pk_mul_f32 v[22:23], v[6:7], v[14:15] op_sel:[1,1] op_sel_hi:[1,0]
	v_mul_f32_e32 v0, v9, v17
	v_pk_mul_f32 v[20:21], v[6:7], v[14:15]
	v_pk_fma_f32 v[6:7], v[6:7], v[14:15], v[22:23] op_sel_hi:[0,1,1]
	v_pk_fma_f32 v[14:15], v[8:9], v[16:17], v[0:1] op_sel_hi:[1,1,0] neg_lo:[0,0,1] neg_hi:[0,0,1]
	v_mul_f32_e32 v0, v9, v16
	v_pk_fma_f32 v[16:17], v[8:9], v[16:17], v[0:1] op_sel:[0,1,0] op_sel_hi:[1,0,0]
	v_mul_f32_e32 v0, v5, v13
	v_pk_mul_f32 v[8:9], v[2:3], v[10:11]
	v_pk_fma_f32 v[2:3], v[2:3], v[10:11], v[24:25] op_sel_hi:[0,1,1]
	v_pk_fma_f32 v[10:11], v[4:5], v[12:13], v[0:1] op_sel_hi:[1,1,0] neg_lo:[0,0,1] neg_hi:[0,0,1]
	v_mul_f32_e32 v0, v5, v12
	v_pk_fma_f32 v[12:13], v[4:5], v[12:13], v[0:1] op_sel:[0,1,0] op_sel_hi:[1,0,0]
	v_sub_f32_e32 v2, v8, v24
	v_sub_f32_e32 v6, v20, v22
	v_mov_b32_e32 v4, v10
	v_mov_b32_e32 v5, v12
	v_mov_b32_e32 v8, v14
	v_mov_b32_e32 v9, v16
	s_branch .LBB0_714
